# P5 entry: each block touches its two residual x tiles (one dword per 128-B line) so the epilogue reads hit the memory-side cache; on top of v69
# baseline (speedup 1.0000x reference)
;     __device__ bool next(int i, Unit& u) const { if (i >= 2) return false; const int x = c & 7, j = c >> 3; u.pm = 64 * i + 8 * x + (j >> 2); u.pn = j & 3; u.ao = 0; u.bo = 0; u.ks = 0; return true; }
; #define PG8_WAIT_V(n) asm volatile("s_waitcnt vmcnt(" #n ")" ::: "memory")
; #define PG8_BAR __builtin_amdgcn_s_barrier()
; template <class Epi, class Sched, bool ALIGN_EPI, bool SP2>
; __device__ __forceinline__ void gemm_phase(LAS unsigned char* lds, const Gemm g, const Sched& S, const Epi& E) {
;     int tid = threadIdx.x; asm volatile("" : "+v"(tid));
;     const int wid = __builtin_amdgcn_readfirstlane(tid >> 6), lane = tid & 63, wr = wid >> 2, wc = wid & 3, fr = lane & 15, fq = lane >> 4;
;     const int K = g.K, nt = K / BK, lda = g.lda;
;     unsigned voffA[2], voffB[2];
; #pragma unroll
;     for (int i = 0; i < 2; ++i) { int R, C; stage_rc(tid * 16 + i * 8192, R, C); const int Rb = (R & ~31) + perm32(R & 31);
;         voffA[i] = (unsigned)(R * lda + C) * 2u; voffB[i] = (unsigned)(Rb * g.ldb + C) * 2u; }
;     const size_t kstep = (size_t)(BK * 2);
;     const size_t hstepA = (size_t)HALF * lda * 2, hstepB = (size_t)HALF * g.ldb * 2;
;     const size_t tstepA = 2 * hstepA, tstepB = 2 * hstepB;
;     const unsigned ldsw = (unsigned)wid * 1024u;
;     const int aoff = lds_byte(wr * 64 + fr, fq * 8), boff = lds_byte(wc * 32 + fr, fq * 8);
;     ...
;     Unit cur, nxt; int ui = 0;
;     if (!S.next(0, cur)) return;
;     f32x4 acc[2][2][4][2];
; #pragma unroll
;     for (int a = 0; a < 2; ++a)
; #pragma unroll
;         for (int b = 0; b < 2; ++b)
; #pragma unroll
;             for (int m = 0; m < 4; ++m)
; #pragma unroll
;                 for (int n = 0; n < 2; ++n) acc[a][b][m][n] = (f32x4){0.f, 0.f, 0.f, 0.f};
;     bf16x8 At[4][2], B0[2][2], B1[2][2];
;     const char* cA = (const char*)g.A + (size_t)cur.pm * tstepA + (size_t)cur.ao * 2; const char* cB = (const char*)g.Bt + (size_t)cur.pn * tstepB + (size_t)cur.bo * 2;
;     if constexpr (SP2) {
;         PG8_STAGE(PG8_SB(0, 0), cB, voffB); PG8_STAGE(PG8_SB(0, 1), cB + hstepB, voffB); PG8_STAGE(PG8_SA(0, 0), cA, voffA); PG8_STAGE(PG8_SA(0, 1), cA + hstepA, voffA);
;         if (wr == 1) PG8_BAR;
;         PG8_WAIT_V(2); PG8_BAR;
;         PG8_STAGE(PG8_SB(1, 0), cB + kstep, voffB); PG8_STAGE(PG8_SA(1, 0), cA + kstep, voffA); PG8_STAGE(PG8_SB(1, 1), cB + hstepB + kstep, voffB);
.LBB0_1206:
	s_or_b64 exec, exec, s[0:1]
	v_mov_b32_e32 v9, v180
	s_waitcnt lgkmcnt(0)
	s_barrier
	s_and_b32 s98, s2, 7
	s_lshr_b32 s99, s2, 3
	s_lshr_b32 s100, s99, 2
	s_lshl3_add_u32 s98, s98, s100
	s_and_b32 s99, s99, 3
	s_lshl_b32 s98, s98, 20
	s_lshl_b32 s99, s99, 10
	s_add_u32 s100, s98, s99
	s_add_u32 s98, s36, s100
	s_addc_u32 s99, s37, 0
	v_lshrrev_b32_e32 v218, 3, v180
	v_and_b32_e32 v219, 7, v180
	v_lshlrev_b32_e32 v218, 12, v218
	v_lshl_or_b32 v218, v219, 7, v218
	global_load_dword v220, v218, s[98:99]
	s_add_u32 s98, s98, 0x40000
	s_addc_u32 s99, s99, 0
	global_load_dword v220, v218, s[98:99]
	s_add_u32 s98, s98, 0x40000
	s_addc_u32 s99, s99, 0
	global_load_dword v220, v218, s[98:99]
	s_add_u32 s98, s98, 0x40000
	s_addc_u32 s99, s99, 0
	global_load_dword v220, v218, s[98:99]
	s_add_u32 s98, s98, 0x3f40000
	s_addc_u32 s99, s99, 0
	global_load_dword v220, v218, s[98:99]
	s_add_u32 s98, s98, 0x40000
	s_addc_u32 s99, s99, 0
	global_load_dword v220, v218, s[98:99]
	s_add_u32 s98, s98, 0x40000
	s_addc_u32 s99, s99, 0
	global_load_dword v220, v218, s[98:99]
	s_add_u32 s98, s98, 0x40000
	s_addc_u32 s99, s99, 0
	global_load_dword v220, v218, s[98:99]
	s_mov_b32 s4, 0xfffe0
	v_ashrrev_i32_e32 v1, 31, v9
	v_lshrrev_b32_e32 v1, 26, v1
	v_add_u32_e32 v1, v9, v1
	v_ashrrev_i32_e32 v8, 6, v1
	v_bfe_i32 v1, v9, 27, 1
	v_lshlrev_b32_e32 v0, 4, v9
	v_lshrrev_b32_e32 v1, 22, v1
	v_add_u32_e32 v1, v0, v1
	v_and_b32_e32 v1, 0xfffffc00, v1
	v_sub_u32_e32 v1, v0, v1
	v_lshrrev_b32_e32 v2, 4, v1
	v_bitop3_b32 v1, v2, v1, 32 bitop3:0x6c
	v_ashrrev_i32_e32 v3, 31, v1
	v_lshrrev_b32_e32 v3, 26, v3
	v_add_u32_e32 v3, v1, v3
	v_lshlrev_b32_e32 v2, 3, v8
	v_ashrrev_i32_e32 v10, 6, v3
	v_and_b32_e32 v3, 0xc0, v3
	v_and_b32_e32 v2, -16, v2
	v_sub_u32_e32 v1, v1, v3
	v_mov_b32_e32 v3, 1
	v_add_u32_e32 v2, v10, v2
	v_lshlrev_b32_e32 v4, 5, v8
	v_ashrrev_i16_sdwa v1, v3, sext(v1) dst_sel:DWORD dst_unused:UNUSED_PAD src0_sel:DWORD src1_sel:BYTE_0
	v_and_b32_e32 v11, 32, v4
	v_bfe_i32 v12, v1, 0, 16
	v_lshlrev_b32_e32 v4, 1, v2
	v_lshrrev_b32_e32 v5, 2, v2
	v_and_b32_e32 v6, 3, v10
	s_movk_i32 s1, 0x1c00
	v_add_u32_e32 v1, v11, v12
	v_and_b32_e32 v4, 24, v4
	v_and_b32_e32 v5, 4, v5
	v_and_or_b32 v6, v2, s4, v6
	v_mul_lo_u32 v2, v2, s1
	v_or3_b32 v4, v6, v5, v4
	v_add_lshl_u32 v144, v1, v2, 1
	v_lshlrev_b32_e32 v1, 1, v1
	v_add_u32_e32 v0, 0x2000, v0
	v_lshl_add_u32 v146, v4, 12, v1
	v_ashrrev_i32_e32 v1, 31, v0
	v_lshrrev_b32_e32 v1, 22, v1
	v_add_u32_e32 v1, v0, v1
	v_ashrrev_i32_e32 v13, 10, v1
	v_mul_i32_i24_e32 v1, 0x400, v13
	v_sub_u32_e32 v0, v0, v1
	v_lshrrev_b32_e32 v1, 4, v0
	v_bitop3_b32 v0, v1, v0, 32 bitop3:0x6c
	v_ashrrev_i32_e32 v2, 31, v0
	v_lshrrev_b32_e32 v2, 26, v2
	v_lshlrev_b32_e32 v1, 3, v13
	v_add_u32_e32 v2, v0, v2
	v_and_b32_e32 v1, -16, v1
	v_ashrrev_i32_e32 v14, 6, v2
	v_lshlrev_b32_e32 v4, 5, v13
	v_add_u32_e32 v1, v14, v1
	v_and_b32_e32 v15, 32, v4
	v_and_b32_e32 v4, 3, v14
	s_add_u32 s50, s28, 0x1dc00000
	v_readfirstlane_b32 s0, v9
	v_and_or_b32 v4, v1, s4, v4
	v_readlane_b32 s4, v254, 3
	s_addc_u32 s51, s29, 0
	s_ashr_i32 s5, s0, 6
	v_and_b32_e32 v2, 0xc0, v2
	s_and_b32 s53, s4, 56
	s_ashr_i32 s4, s2, 5
	s_bfe_u32 s55, s2, 0x20003
	v_sub_u32_e32 v0, v0, v2
	s_ashr_i32 s16, s0, 8
	s_add_i32 s53, s53, s4
	s_lshl_b32 s54, s5, 10
	s_lshl_b32 s4, s55, 20
	v_ashrrev_i16_sdwa v0, v3, sext(v0) dst_sel:DWORD dst_unused:UNUSED_PAD src0_sel:DWORD src1_sel:BYTE_0
	s_add_u32 s6, s50, s4
	v_bfe_i32 v16, v0, 0, 16
	v_lshlrev_b32_e32 v2, 1, v1
	v_lshrrev_b32_e32 v3, 2, v1
	s_addc_u32 s7, s51, 0
	s_add_i32 s56, s54, 0
	v_add_u32_e32 v0, v15, v16
	v_and_b32_e32 v2, 24, v2
	v_and_b32_e32 v3, 4, v3
	v_mul_lo_u32 v1, v1, s1
	s_add_i32 m0, s56, 0x10000
	v_or3_b32 v2, v4, v3, v2
	v_add_lshl_u32 v148, v0, v1, 1
	v_lshlrev_b32_e32 v0, 1, v0
	global_load_lds_dwordx4 v146, s[6:7]
	s_add_i32 m0, s56, 0x12000
	v_lshl_add_u32 v150, v2, 12, v0
	s_add_u32 s8, s6, 0x80000
	global_load_lds_dwordx4 v150, s[6:7]
	s_addc_u32 s9, s7, 0
	s_add_i32 m0, s56, 0x14000
	s_mul_i32 s11, s53, 0x380000
	global_load_lds_dwordx4 v146, s[8:9]
	s_add_i32 m0, s56, 0x16000
	s_mul_hi_i32 s10, s53, 0x380000
	v_mov_b32_e32 v153, 0
	global_load_lds_dwordx4 v150, s[8:9]
	s_add_u32 s8, s28, s11
	s_addc_u32 s9, s29, s10
	v_mov_b32_e32 v145, v153
	s_mov_b64 s[10:11], 0x800
	s_add_u32 s42, s8, 0x800
	v_lshl_add_u64 v[0:1], s[8:9], 0, v[144:145]
	s_addc_u32 s43, s9, 0
	v_lshl_add_u64 v[2:3], v[0:1], 0, s[10:11]
	s_mov_b32 m0, s56
	v_mov_b32_e32 v149, v153
	s_add_i32 s57, s56, 0x2000
	global_load_lds_dwordx4 v[2:3], off
	v_lshl_add_u64 v[2:3], s[8:9], 0, v[148:149]
	s_add_u32 s8, s8, 0x1c0800
	v_lshl_add_u64 v[4:5], v[2:3], 0, s[10:11]
	s_mov_b32 m0, s57
	s_addc_u32 s9, s9, 0
	s_add_i32 s58, s56, 0x4000
	global_load_lds_dwordx4 v[4:5], off
	s_mov_b32 m0, s58
	s_add_i32 s59, s56, 0x6000
	global_load_lds_dwordx4 v144, s[8:9]
	s_mov_b32 m0, s59
	v_mov_b32_e32 v147, v153
	global_load_lds_dwordx4 v148, s[8:9]
	v_mov_b32_e32 v151, v153
	s_cmp_eq_u32 s16, 1
	v_lshl_add_u64 v[4:5], s[6:7], 0, v[146:147]
	s_cselect_b64 s[8:9], -1, 0
	s_cmp_lg_u32 s16, 1
	v_lshl_add_u64 v[6:7], s[6:7], 0, v[150:151]
	s_cbranch_scc1 .LBB0_1208
	s_barrier
